# RWKV per-block overhead trimmed: m0 from a pre-combined ring offset, VGPR publish counter, inline fast poll with out-of-line slow loop
# speedup vs baseline: 1.0200x; 1.0044x over previous
; #define RW_LANDED(WN, XN, KN, VN) asm volatile("s_waitcnt lgkmcnt(0)" : "+v"(WN), "+v"(XN), "+v"(KN), "+v"(VN) :: "memory")
; #define RW_DMA4(B) RW_DMA_ONLY(B); RW_DMA_ONLY((B) + 1); RW_DMA_ONLY((B) + 2); RW_DMA_ONLY((B) + 3)
; template <int DIR>
; DEVINL void rwkv_scan_dir(const Params& p, int task, int lane, int wave) {
;   const int b = (task >> 8) & 1, head = (task >> 4) & 15, rg = task & 15;
;   const int seg = lane & 15, rl = lane >> 4, row = rg * 4 + rl;
;   constexpr int DIST = 24;
;   constexpr int WOFS = DIR ? 8 : 0;
;   const char* recbase = p.ws + O_REC + ((long)(b * 16 + head) * 4096) * 1024 + lane * 16;
;   const unsigned ring_lds = (unsigned)(unsigned long)(__attribute__((address_space(3))) char*)(dynsmem + wave * 32768);
;   const unsigned ring_u = __builtin_amdgcn_readfirstlane(ring_lds);
;   const unsigned a_seg = ring_lds + seg * 64;
;   const unsigned a_v = ring_lds + (row >> 2) * 64 + 48 + (row & 3) * 2;
;   u16* yo = (u16*)(p.ws + (DIR ? O_YB : O_YSUM)) + ((long)b * 4096) * 1024 + head * 64 + row;
;   float s0 = 0.f, s1 = 0.f, s2 = 0.f, s3 = 0.f;
;   float ykeep = 0.f;
;   const char* recdir = recbase + (DIR ? (long)4095 * 1024 : 0);
;     ...
;   u32x2 WvA, WvB; u32x4 XA, XB, KrA, KrB; unsigned vhA, vhB;
;   RW_DMA4(0); RW_DMA4(4); RW_DMA4(8); RW_DMA4(12); RW_DMA4(16); RW_DMA4(20);
;   RW_READ(0, WvA, XA, KrA, vhA, 23);
;   RW_LANDED(WvA, XA, KrA, vhA);
.Lrw_task:
	s_cmp_ge_u32 s7, 0x400
	s_cbranch_scc1 .Lrw_done
	s_and_b32 s24, s7, 15
	s_bfe_u32 s26, s7, 0x40004
	s_bfe_u32 s32, s7, 0x10008
	s_lshr_b32 s36, s7, 9
	s_lshl_b32 s3, s32, 4
	s_add_u32 s3, s3, s26
	s_lshl_b32 s3, s3, 22
	s_add_u32 s10, s92, s3
	s_addc_u32 s11, s93, 0
	s_add_u32 s10, s10, 0xf400000
	s_addc_u32 s11, s11, 0
	s_lshl_b32 s3, s32, 23
	s_lshl_b32 s37, s26, 7
	s_add_u32 s3, s3, s37
	s_add_u32 s12, s92, s3
	s_addc_u32 s13, s93, 0
	s_lshl_b32 s3, s24, 3
	v_lshl_add_u32 v8, v4, 1, s3
	s_lshl_b32 s37, s24, 4
	s_lshl_b32 s39, s6, 12
	s_cmp_lg_u32 s36, 0
	s_cbranch_scc1 .Lrw_bwd
	s_add_u32 s12, s12, 0x2000000
	s_addc_u32 s13, s13, 0
	v_lshl_add_u32 v8, v3, 11, v8
	s_add_u32 s10, s10, s39
	s_addc_u32 s11, s11, 0
	s_mov_b32 s40, s39
	s_mov_b32 s41, 0
	v_lshlrev_b32_e32 v6, 4, v3
	s_add_u32 s3, s37, 0x300
	v_lshl_add_u32 v7, v4, 1, s3
	s_add_u32 s41, s40, s41
	s_and_b32 s41, s41, 0x1ffff
	s_add_u32 m0, s41, 16
	s_nop 0
	global_load_lds_dwordx4 v5, s[10:11] offset:0
	global_load_lds_dwordx4 v5, s[10:11] offset:1024
	global_load_lds_dwordx4 v5, s[10:11] offset:2048
	global_load_lds_dwordx4 v5, s[10:11] offset:3072
	s_add_u32 s10, s10, 0x4000
	s_addc_u32 s11, s11, 0
	s_add_u32 s41, s41, 0x4000
	s_and_b32 s41, s41, 0x1ffff
	s_add_u32 m0, s41, 16
	s_nop 0
	global_load_lds_dwordx4 v5, s[10:11] offset:0
	global_load_lds_dwordx4 v5, s[10:11] offset:1024
	global_load_lds_dwordx4 v5, s[10:11] offset:2048
	global_load_lds_dwordx4 v5, s[10:11] offset:3072
	s_add_u32 s10, s10, 0x4000
	s_addc_u32 s11, s11, 0
	s_add_u32 s41, s41, 0x4000
	s_and_b32 s41, s41, 0x1ffff
	s_add_u32 m0, s41, 16
	s_nop 0
	global_load_lds_dwordx4 v5, s[10:11] offset:0
	global_load_lds_dwordx4 v5, s[10:11] offset:1024
	global_load_lds_dwordx4 v5, s[10:11] offset:2048
	global_load_lds_dwordx4 v5, s[10:11] offset:3072
	s_add_u32 s10, s10, 0x4000
	s_addc_u32 s11, s11, 0
	s_add_u32 s41, s41, 0x4000
	s_and_b32 s41, s41, 0x1ffff
	s_waitcnt vmcnt(0)
	v_mov_b32_e32 v10, 0
	v_mov_b32_e32 v11, 0
	v_mov_b32_e32 v12, 0
	v_mov_b32_e32 v13, 0
	s_mov_b32 s14, 0
	s_add_u32 s3, s15, 2
	v_mov_b32_e32 v69, s3
	ds_write_b32 v23, v69
	s_add_u32 s43, s15, 2
	ds_read_b128 v[100:103], v9
	s_waitcnt lgkmcnt(0)
	v_min3_u32 v100, v100, v101, v102
	v_min_u32_e32 v100, v100, v103
	s_nop 0
	v_readfirstlane_b32 s24, v100
	s_nop 0
	s_cmp_ge_u32 s24, s43
	s_cbranch_scc0 .Lrw_slow_d0p

; DEVINL u16 f2bf(float a) { return (u16)(pk2(a, 0.f) & 0xffffu); }
; #define RW_STEP2(B) RW_STEP(B, WvA, XA, KrA, vhA, WvB, XB, KrB, vhB); RW_STEP((B) + 1, WvB, XB, KrB, vhB, WvA, XA, KrA, vhA)
; #define RW_STEP4(B) RW_STEP2(B); RW_STEP2((B) + 2)
; template <int DIR>
; DEVINL void rwkv_scan_dir(const Params& p, int task, int lane, int wave) {
;     ...
;     if (st > 0) { const int q0 = st - 16 + seg; yo[(long)(DIR ? (4095 - q0) : q0) * 1024] = f2bf(ykeep); }
;     RW_STEP(1, WvB, XB, KrB, vhB, WvA, XA, KrA, vhA);
;     RW_STEP2(2); RW_STEP4(4); RW_STEP4(8); RW_STEP4(12);
;     RW_STEP(16, WvA, XA, KrA, vhA, WvB, XB, KrB, vhB);
;     { const int q0 = st + seg; yo[(long)(DIR ? (4095 - q0) : q0) * 1024] = f2bf(ykeep); }
.Lrw_nofull_d0:
	s_waitcnt vmcnt(1)
	v_add_u32_e32 v69, 1, v69
	ds_write_b32 v23, v69
	s_add_u32 s43, s15, 2
	v_min3_u32 v100, v100, v101, v102
	v_min_u32_e32 v100, v100, v103
	s_nop 0
	v_readfirstlane_b32 s24, v100
	s_nop 0
	s_cmp_ge_u32 s24, s43
	s_cbranch_scc0 .Lrw_slow_d0
.Lrw_ready_d0:
	s_add_u32 m0, s41, 16
	s_nop 0
	global_load_lds_dwordx4 v5, s[10:11] offset:0
	global_load_lds_dwordx4 v5, s[10:11] offset:1024
	global_load_lds_dwordx4 v5, s[10:11] offset:2048
	global_load_lds_dwordx4 v5, s[10:11] offset:3072
	s_add_u32 s10, s10, 0x4000
	s_addc_u32 s11, s11, 0
	s_add_u32 s41, s41, 0x4000
	s_and_b32 s41, s41, 0x1ffff
	ds_read_b64 v[72:73], v6 offset:2064
	ds_read_b128 v[74:77], v6 offset:2320
	ds_read_b128 v[78:81], v6 offset:2576
	ds_read_u16 v82, v7 offset:2064
	v_fma_mix_f32 v14, v10, v26, 0 op_sel:[0,0,0] op_sel_hi:[0,1,0]
	v_fma_mix_f32 v63, v10, v92, 0 op_sel:[0,0,0] op_sel_hi:[0,1,0]
	v_fma_mix_f32 v14, v11, v26, v14 op_sel:[0,1,0] op_sel_hi:[0,1,0]
	v_fma_mix_f32 v63, v11, v92, v63 op_sel:[0,1,0] op_sel_hi:[0,1,0]
	v_fma_mix_f32 v14, v12, v27, v14 op_sel:[0,0,0] op_sel_hi:[0,1,0]
	v_fma_mix_f32 v63, v12, v93, v63 op_sel:[0,0,0] op_sel_hi:[0,1,0]
	v_fma_mix_f32 v14, v13, v27, v14 op_sel:[0,1,0] op_sel_hi:[0,1,0]
	v_fma_mix_f32 v16, v10, v24, 0 op_sel:[0,0,0] op_sel_hi:[0,1,0]
	v_fma_mix_f32 v17, v11, v24, 0 op_sel:[0,1,0] op_sel_hi:[0,1,0]
	v_add_f32_dpp v20, v14, v14 quad_perm:[1,0,3,2] row_mask:0xf bank_mask:0xf bound_ctrl:1
	v_fma_mix_f32 v63, v13, v93, v63 op_sel:[0,1,0] op_sel_hi:[0,1,0]
	v_fma_mix_f32 v18, v12, v25, 0 op_sel:[0,0,0] op_sel_hi:[0,1,0]
	v_add_f32_dpp v20, v20, v20 quad_perm:[2,3,0,1] row_mask:0xf bank_mask:0xf bound_ctrl:1
	v_fma_mix_f32 v19, v13, v25, 0 op_sel:[0,1,0] op_sel_hi:[0,1,0]
	v_fma_mix_f32 v16, v34, v30, v16 op_sel:[0,0,0] op_sel_hi:[1,1,0]
	v_add_f32_dpp v20, v20, v20 row_half_mirror row_mask:0xf bank_mask:0xf bound_ctrl:1
	v_fma_mix_f32 v17, v34, v30, v17 op_sel:[0,1,0] op_sel_hi:[1,1,0]
	v_fma_mix_f32 v18, v34, v31, v18 op_sel:[0,0,0] op_sel_hi:[1,1,0]
	v_add_f32_dpp v20, v20, v20 row_mirror row_mask:0xf bank_mask:0xf bound_ctrl:1
	v_fma_mix_f32 v19, v34, v31, v19 op_sel:[0,1,0] op_sel_hi:[1,1,0]
	v_fma_mix_f32 v10, v20, v28, v16 op_sel:[0,0,0] op_sel_hi:[0,1,0]
	v_fma_mix_f32 v11, v20, v28, v17 op_sel:[0,1,0] op_sel_hi:[0,1,0]
	v_fma_mix_f32 v12, v20, v29, v18 op_sel:[0,0,0] op_sel_hi:[0,1,0]
	v_fma_mix_f32 v13, v20, v29, v19 op_sel:[0,1,0] op_sel_hi:[0,1,0]
	s_waitcnt lgkmcnt(4)
	s_cmp_eq_u32 s14, 0
	s_cbranch_scc1 .Lrw_skip_d0
	v_add_f32_dpp v48, v48, v48 row_ror:8 row_mask:0xf bank_mask:0x3
	v_add_f32_dpp v49, v49, v49 row_ror:8 row_mask:0xf bank_mask:0x3
	v_add_f32_dpp v50, v50, v50 row_ror:8 row_mask:0xf bank_mask:0x3
	v_add_f32_dpp v51, v51, v51 row_ror:8 row_mask:0xf bank_mask:0x3
	v_add_f32_dpp v52, v52, v52 row_ror:8 row_mask:0xf bank_mask:0x3
	v_add_f32_dpp v53, v53, v53 row_ror:8 row_mask:0xf bank_mask:0x3
	v_add_f32_dpp v54, v54, v54 row_ror:8 row_mask:0xf bank_mask:0x3
	v_add_f32_dpp v55, v55, v55 row_ror:8 row_mask:0xf bank_mask:0x3
	v_add_f32_dpp v48, v56, v56 row_ror:8 row_mask:0xf bank_mask:0xc
	v_add_f32_dpp v49, v57, v57 row_ror:8 row_mask:0xf bank_mask:0xc
	v_add_f32_dpp v50, v58, v58 row_ror:8 row_mask:0xf bank_mask:0xc
	v_add_f32_dpp v51, v59, v59 row_ror:8 row_mask:0xf bank_mask:0xc
	v_add_f32_dpp v52, v60, v60 row_ror:8 row_mask:0xf bank_mask:0xc
	v_add_f32_dpp v53, v61, v61 row_ror:8 row_mask:0xf bank_mask:0xc
	v_add_f32_dpp v54, v62, v62 row_ror:8 row_mask:0xf bank_mask:0xc
	v_add_f32_dpp v55, v63, v63 row_ror:8 row_mask:0xf bank_mask:0xc
	v_add_f32_dpp v48, v48, v48 row_ror:12 row_mask:0xf bank_mask:0x5
	v_add_f32_dpp v49, v49, v49 row_ror:12 row_mask:0xf bank_mask:0x5
	v_add_f32_dpp v50, v50, v50 row_ror:12 row_mask:0xf bank_mask:0x5
	v_add_f32_dpp v51, v51, v51 row_ror:12 row_mask:0xf bank_mask:0x5
	v_add_f32_dpp v48, v52, v52 row_ror:4 row_mask:0xf bank_mask:0xa
	v_add_f32_dpp v49, v53, v53 row_ror:4 row_mask:0xf bank_mask:0xa
	v_add_f32_dpp v50, v54, v54 row_ror:4 row_mask:0xf bank_mask:0xa
	v_add_f32_dpp v51, v55, v55 row_ror:4 row_mask:0xf bank_mask:0xa
	v_add_f32_dpp v64, v48, v48 quad_perm:[2,3,0,1] row_mask:0xf bank_mask:0xf bound_ctrl:1
	v_add_f32_dpp v65, v50, v50 quad_perm:[2,3,0,1] row_mask:0xf bank_mask:0xf bound_ctrl:1
	v_cndmask_b32_e64 v56, v64, v65, s[50:51]
	v_add_f32_dpp v64, v49, v49 quad_perm:[2,3,0,1] row_mask:0xf bank_mask:0xf bound_ctrl:1
	v_add_f32_dpp v65, v51, v51 quad_perm:[2,3,0,1] row_mask:0xf bank_mask:0xf bound_ctrl:1
	v_cndmask_b32_e64 v57, v64, v65, s[50:51]
	v_add_f32_dpp v64, v56, v56 quad_perm:[1,0,3,2] row_mask:0xf bank_mask:0xf bound_ctrl:1
	s_nop 0
	v_add_f32_dpp v65, v57, v57 quad_perm:[1,0,3,2] row_mask:0xf bank_mask:0xf bound_ctrl:1
	v_cndmask_b32_e64 v66, v64, v65, s[48:49]
	v_cvt_pk_bf16_f32 v66, v66, v66
	global_store_short v8, v66, s[12:13]
	s_add_u32 s12, s12, 0x8000
	s_addc_u32 s13, s13, 0

; #define RW_LANDED(WN, XN, KN, VN) asm volatile("s_waitcnt lgkmcnt(0)" : "+v"(WN), "+v"(XN), "+v"(KN), "+v"(VN) :: "memory")
; #define RW_DMA4(B) RW_DMA_ONLY(B); RW_DMA_ONLY((B) + 1); RW_DMA_ONLY((B) + 2); RW_DMA_ONLY((B) + 3)
; template <int DIR>
; DEVINL void rwkv_scan_dir(const Params& p, int task, int lane, int wave) {
;     ...
;   const char* recbase = p.ws + O_REC + ((long)(b * 16 + head) * 4096) * 1024 + lane * 16;
;   const unsigned ring_lds = (unsigned)(unsigned long)(__attribute__((address_space(3))) char*)(dynsmem + wave * 32768);
;   const unsigned ring_u = __builtin_amdgcn_readfirstlane(ring_lds);
;   const unsigned a_seg = ring_lds + seg * 64;
;   const unsigned a_v = ring_lds + (row >> 2) * 64 + 48 + (row & 3) * 2;
;   u16* yo = (u16*)(p.ws + (DIR ? O_YB : O_YSUM)) + ((long)b * 4096) * 1024 + head * 64 + row;
;   float s0 = 0.f, s1 = 0.f, s2 = 0.f, s3 = 0.f;
;   float ykeep = 0.f;
;   const char* recdir = recbase + (DIR ? (long)4095 * 1024 : 0);
;     ...
;   u32x2 WvA, WvB; u32x4 XA, XB, KrA, KrB; unsigned vhA, vhB;
;   RW_DMA4(0); RW_DMA4(4); RW_DMA4(8); RW_DMA4(12); RW_DMA4(16); RW_DMA4(20);
;   RW_READ(0, WvA, XA, KrA, vhA, 23);
;   RW_LANDED(WvA, XA, KrA, vhA);
.Lrw_bwd:
	s_add_u32 s12, s12, 0x1f700000
	s_addc_u32 s13, s13, 0
	v_sub_u32_e32 v69, 0xfff, v3
	v_lshl_add_u32 v8, v69, 11, v8
	s_add_u32 s10, s10, 0x3ff000
	s_addc_u32 s11, s11, 0
	s_sub_u32 s10, s10, s39
	s_subb_u32 s11, s11, 0
	s_sub_u32 s40, 0x1f000, s39
	s_mov_b32 s41, 0
	v_lshlrev_b32_e32 v6, 4, v3
	v_add_u32_e32 v6, 0x1c000, v6
	s_add_u32 s3, s37, 0x1c300
	v_lshl_add_u32 v7, v4, 1, s3
	s_add_u32 s41, s40, s41
	s_and_b32 s41, s41, 0x1ffff
	s_add_u32 m0, s41, 16
	s_nop 0
	global_load_lds_dwordx4 v5, s[10:11] offset:0
	global_load_lds_dwordx4 v5, s[10:11] offset:1024
	global_load_lds_dwordx4 v5, s[10:11] offset:2048
	global_load_lds_dwordx4 v5, s[10:11] offset:3072
	s_sub_u32 s10, s10, 0x4000
	s_subb_u32 s11, s11, 0
	s_sub_u32 s41, s41, 0x4000
	s_and_b32 s41, s41, 0x1ffff
	s_add_u32 m0, s41, 16
	s_nop 0
	global_load_lds_dwordx4 v5, s[10:11] offset:0
	global_load_lds_dwordx4 v5, s[10:11] offset:1024
	global_load_lds_dwordx4 v5, s[10:11] offset:2048
	global_load_lds_dwordx4 v5, s[10:11] offset:3072
	s_sub_u32 s10, s10, 0x4000
	s_subb_u32 s11, s11, 0
	s_sub_u32 s41, s41, 0x4000
	s_and_b32 s41, s41, 0x1ffff
	s_add_u32 m0, s41, 16
	s_nop 0
	global_load_lds_dwordx4 v5, s[10:11] offset:0
	global_load_lds_dwordx4 v5, s[10:11] offset:1024
	global_load_lds_dwordx4 v5, s[10:11] offset:2048
	global_load_lds_dwordx4 v5, s[10:11] offset:3072
	s_sub_u32 s10, s10, 0x4000
	s_subb_u32 s11, s11, 0
	s_sub_u32 s41, s41, 0x4000
	s_and_b32 s41, s41, 0x1ffff
	s_waitcnt vmcnt(0)
	v_mov_b32_e32 v10, 0
	v_mov_b32_e32 v11, 0
	v_mov_b32_e32 v12, 0
	v_mov_b32_e32 v13, 0
	s_mov_b32 s14, 0
	s_add_u32 s3, s15, 2
	v_mov_b32_e32 v69, s3
	ds_write_b32 v23, v69
	s_add_u32 s43, s15, 2
	ds_read_b128 v[100:103], v9
	s_waitcnt lgkmcnt(0)
	v_min3_u32 v100, v100, v101, v102
	v_min_u32_e32 v100, v100, v103
	s_nop 0
	v_readfirstlane_b32 s24, v100
	s_nop 0
	s_cmp_ge_u32 s24, s43
	s_cbranch_scc0 .Lrw_slow_d1p

; DEVINL u16 f2bf(float a) { return (u16)(pk2(a, 0.f) & 0xffffu); }
; #define RW_STEP2(B) RW_STEP(B, WvA, XA, KrA, vhA, WvB, XB, KrB, vhB); RW_STEP((B) + 1, WvB, XB, KrB, vhB, WvA, XA, KrA, vhA)
; #define RW_STEP4(B) RW_STEP2(B); RW_STEP2((B) + 2)
; template <int DIR>
; DEVINL void rwkv_scan_dir(const Params& p, int task, int lane, int wave) {
;     ...
;     if (st > 0) { const int q0 = st - 16 + seg; yo[(long)(DIR ? (4095 - q0) : q0) * 1024] = f2bf(ykeep); }
;     RW_STEP(1, WvB, XB, KrB, vhB, WvA, XA, KrA, vhA);
;     RW_STEP2(2); RW_STEP4(4); RW_STEP4(8); RW_STEP4(12);
;     RW_STEP(16, WvA, XA, KrA, vhA, WvB, XB, KrB, vhB);
;     { const int q0 = st + seg; yo[(long)(DIR ? (4095 - q0) : q0) * 1024] = f2bf(ykeep); }
.Lrw_ready_d1:
	s_add_u32 m0, s41, 16
	s_nop 0
	global_load_lds_dwordx4 v5, s[10:11] offset:0
	global_load_lds_dwordx4 v5, s[10:11] offset:1024
	global_load_lds_dwordx4 v5, s[10:11] offset:2048
	global_load_lds_dwordx4 v5, s[10:11] offset:3072
	s_sub_u32 s10, s10, 0x4000
	s_subb_u32 s11, s11, 0
	s_sub_u32 s41, s41, 0x4000
	s_and_b32 s41, s41, 0x1ffff
	ds_read_b64 v[72:73], v6 offset:13336
	ds_read_b128 v[74:77], v6 offset:13584
	ds_read_b128 v[78:81], v6 offset:13840
	ds_read_u16 v82, v7 offset:13328
	v_fma_mix_f32 v14, v10, v26, 0 op_sel:[0,0,0] op_sel_hi:[0,1,0]
	v_fma_mix_f32 v63, v10, v92, 0 op_sel:[0,0,0] op_sel_hi:[0,1,0]
	v_fma_mix_f32 v14, v11, v26, v14 op_sel:[0,1,0] op_sel_hi:[0,1,0]
	v_fma_mix_f32 v63, v11, v92, v63 op_sel:[0,1,0] op_sel_hi:[0,1,0]
	v_fma_mix_f32 v14, v12, v27, v14 op_sel:[0,0,0] op_sel_hi:[0,1,0]
	v_fma_mix_f32 v63, v12, v93, v63 op_sel:[0,0,0] op_sel_hi:[0,1,0]
	v_fma_mix_f32 v14, v13, v27, v14 op_sel:[0,1,0] op_sel_hi:[0,1,0]
	v_fma_mix_f32 v16, v10, v24, 0 op_sel:[0,0,0] op_sel_hi:[0,1,0]
	v_fma_mix_f32 v17, v11, v24, 0 op_sel:[0,1,0] op_sel_hi:[0,1,0]
	v_add_f32_dpp v20, v14, v14 quad_perm:[1,0,3,2] row_mask:0xf bank_mask:0xf bound_ctrl:1
	v_fma_mix_f32 v63, v13, v93, v63 op_sel:[0,1,0] op_sel_hi:[0,1,0]
	v_fma_mix_f32 v18, v12, v25, 0 op_sel:[0,0,0] op_sel_hi:[0,1,0]
	v_add_f32_dpp v20, v20, v20 quad_perm:[2,3,0,1] row_mask:0xf bank_mask:0xf bound_ctrl:1
	v_fma_mix_f32 v19, v13, v25, 0 op_sel:[0,1,0] op_sel_hi:[0,1,0]
	v_fma_mix_f32 v16, v34, v30, v16 op_sel:[0,0,0] op_sel_hi:[1,1,0]
	v_add_f32_dpp v20, v20, v20 row_half_mirror row_mask:0xf bank_mask:0xf bound_ctrl:1
	v_fma_mix_f32 v17, v34, v30, v17 op_sel:[0,1,0] op_sel_hi:[1,1,0]
	v_fma_mix_f32 v18, v34, v31, v18 op_sel:[0,0,0] op_sel_hi:[1,1,0]
	v_add_f32_dpp v20, v20, v20 row_mirror row_mask:0xf bank_mask:0xf bound_ctrl:1
	v_fma_mix_f32 v19, v34, v31, v19 op_sel:[0,1,0] op_sel_hi:[1,1,0]
	v_fma_mix_f32 v10, v20, v28, v16 op_sel:[0,0,0] op_sel_hi:[0,1,0]
	v_fma_mix_f32 v11, v20, v28, v17 op_sel:[0,1,0] op_sel_hi:[0,1,0]
	v_fma_mix_f32 v12, v20, v29, v18 op_sel:[0,0,0] op_sel_hi:[0,1,0]
	v_fma_mix_f32 v13, v20, v29, v19 op_sel:[0,1,0] op_sel_hi:[0,1,0]
	s_waitcnt lgkmcnt(4)
	s_cmp_eq_u32 s14, 0
	s_cbranch_scc1 .Lrw_skip_d1
	v_add_f32_dpp v48, v48, v48 row_ror:8 row_mask:0xf bank_mask:0x3
	v_add_f32_dpp v49, v49, v49 row_ror:8 row_mask:0xf bank_mask:0x3
	v_add_f32_dpp v50, v50, v50 row_ror:8 row_mask:0xf bank_mask:0x3
	v_add_f32_dpp v51, v51, v51 row_ror:8 row_mask:0xf bank_mask:0x3
	v_add_f32_dpp v52, v52, v52 row_ror:8 row_mask:0xf bank_mask:0x3
	v_add_f32_dpp v53, v53, v53 row_ror:8 row_mask:0xf bank_mask:0x3
	v_add_f32_dpp v54, v54, v54 row_ror:8 row_mask:0xf bank_mask:0x3
	v_add_f32_dpp v55, v55, v55 row_ror:8 row_mask:0xf bank_mask:0x3
	v_add_f32_dpp v48, v56, v56 row_ror:8 row_mask:0xf bank_mask:0xc
	v_add_f32_dpp v49, v57, v57 row_ror:8 row_mask:0xf bank_mask:0xc
	v_add_f32_dpp v50, v58, v58 row_ror:8 row_mask:0xf bank_mask:0xc
	v_add_f32_dpp v51, v59, v59 row_ror:8 row_mask:0xf bank_mask:0xc
	v_add_f32_dpp v52, v60, v60 row_ror:8 row_mask:0xf bank_mask:0xc
	v_add_f32_dpp v53, v61, v61 row_ror:8 row_mask:0xf bank_mask:0xc
	v_add_f32_dpp v54, v62, v62 row_ror:8 row_mask:0xf bank_mask:0xc
	v_add_f32_dpp v55, v63, v63 row_ror:8 row_mask:0xf bank_mask:0xc
	v_add_f32_dpp v48, v48, v48 row_ror:12 row_mask:0xf bank_mask:0x5
	v_add_f32_dpp v49, v49, v49 row_ror:12 row_mask:0xf bank_mask:0x5
	v_add_f32_dpp v50, v50, v50 row_ror:12 row_mask:0xf bank_mask:0x5
	v_add_f32_dpp v51, v51, v51 row_ror:12 row_mask:0xf bank_mask:0x5
	v_add_f32_dpp v48, v52, v52 row_ror:4 row_mask:0xf bank_mask:0xa
	v_add_f32_dpp v49, v53, v53 row_ror:4 row_mask:0xf bank_mask:0xa
	v_add_f32_dpp v50, v54, v54 row_ror:4 row_mask:0xf bank_mask:0xa
	v_add_f32_dpp v51, v55, v55 row_ror:4 row_mask:0xf bank_mask:0xa
	v_add_f32_dpp v64, v48, v48 quad_perm:[2,3,0,1] row_mask:0xf bank_mask:0xf bound_ctrl:1
	v_add_f32_dpp v65, v50, v50 quad_perm:[2,3,0,1] row_mask:0xf bank_mask:0xf bound_ctrl:1
	v_cndmask_b32_e64 v56, v64, v65, s[50:51]
	v_add_f32_dpp v64, v49, v49 quad_perm:[2,3,0,1] row_mask:0xf bank_mask:0xf bound_ctrl:1
	v_add_f32_dpp v65, v51, v51 quad_perm:[2,3,0,1] row_mask:0xf bank_mask:0xf bound_ctrl:1
	v_cndmask_b32_e64 v57, v64, v65, s[50:51]
	v_add_f32_dpp v64, v56, v56 quad_perm:[1,0,3,2] row_mask:0xf bank_mask:0xf bound_ctrl:1
	s_nop 0
	v_add_f32_dpp v65, v57, v57 quad_perm:[1,0,3,2] row_mask:0xf bank_mask:0xf bound_ctrl:1
	v_cndmask_b32_e64 v66, v64, v65, s[48:49]
	v_cvt_pk_bf16_f32 v66, v66, v66
	global_store_short v8, v66, s[12:13]
	s_sub_u32 s12, s12, 0x8000
	s_subb_u32 s13, s13, 0

.Lrw_slow_d0p:
	s_mov_b32 s42, 0
.Lrw_poll_d0p:
	s_sleep 1
	ds_read_b128 v[100:103], v9
	s_waitcnt lgkmcnt(0)
	v_min3_u32 v100, v100, v101, v102
	v_min_u32_e32 v100, v100, v103
	s_nop 0
	v_readfirstlane_b32 s24, v100
	s_nop 0
	s_cmp_ge_u32 s24, s43
	s_cbranch_scc1 .Lrw_ready_d0p
	s_add_u32 s42, s42, 1
	s_cmp_lt_u32 s42, 0x400
	s_cbranch_scc1 .Lrw_poll_d0p
	s_branch .Lrw_ready_d0p
